# serial kernarg s_loads batched in front of the attention queue and in the table build's first stage
# baseline (speedup 1.0000x reference)
; #define INP(k) ((const float*)(GAS const float*)KARG64(8 * (k)))
; __device__ __forceinline__ void ssm_tables(int g, int part, LAS float* L, bf16* __restrict__ TE, bf16* __restrict__ FT, float* __restrict__ LAM16) {
;     ...
;     const float dt = __expf(INP(6)[g]);
;     if (tid < 64) {
;         const int p = tid; const float are = INP(4)[g * 64 + p], aim = INP(5)[g * 64 + p];
;         for (int k = 0; k <= 16; ++k) {
;             const float mag = __expf(are * dt * (float)k);
;             float rev = aim * dt * (float)k * 0.15915494309189535f; rev -= rintf(rev);
;             lkr[k * 64 + p] = mag * __builtin_amdgcn_cosf(rev); lki[k * 64 + p] = mag * __builtin_amdgcn_sinf(rev);
;         }
;         const float lbr = lkr[64 + p], lbi = lki[64 + p], den = are * are + aim * aim, nre = lbr - 1.f;
;         fr_[p] = (nre * are + lbi * aim) / den; fi_[p] = (lbi * are - nre * aim) / den;
;         if (part == 0) { LAM16[(g * 64 + p) * 2] = lkr[16 * 64 + p]; LAM16[(g * 64 + p) * 2 + 1] = lki[16 * 64 + p]; }
.LBB0_9:
	s_mov_b64 s[10:11], s[0:1]
	s_load_dwordx2 s[14:15], s[10:11], 0xf0
	s_mov_b64 s[10:11], s[0:1]
	s_load_dwordx2 s[10:11], s[10:11], 0xf0
	s_ashr_i32 s12, s33, 3
	s_and_b32 s34, s33, 7
	s_load_dwordx2 s[60:61], s[0:1], 0x38
	s_load_dwordx2 s[62:63], s[0:1], 0x40
	s_load_dwordx2 s[64:65], s[0:1], 0x48
	s_load_dwordx2 s[66:67], s[0:1], 0x50
	s_load_dwordx2 s[72:73], s[0:1], 0x58
	s_load_dwordx2 s[74:75], s[0:1], 0x30
	s_load_dwordx2 s[76:77], s[0:1], 0x20
	s_load_dwordx2 s[88:89], s[0:1], 0x28
	s_lshl_b32 s70, s12, 10
	v_add_u32_e32 v92, s70, v218
	v_lshlrev_b32_e32 v92, 2, v92
	v_lshl_or_b32 v166, s12, 4, v10
	v_lshlrev_b32_e32 v166, 2, v166
	s_waitcnt lgkmcnt(0)
	global_load_dword v94, v92, s[60:61]
	global_load_dword v95, v92, s[62:63]
	global_load_dword v96, v92, s[64:65]
	global_load_dword v97, v92, s[66:67]
	global_load_dword v98, v92, s[60:61] offset:2048
	global_load_dword v99, v92, s[62:63] offset:2048
	global_load_dword v164, v92, s[64:65] offset:2048
	global_load_dword v165, v92, s[66:67] offset:2048
	global_load_dword v93, v166, s[72:73]
	s_mov_b64 s[18:19], s[0:1]
	s_mov_b64 s[20:21], s[0:1]
	s_and_saveexec_b64 s[16:17], s[4:5]
	s_cbranch_execz .LBB0_12
	s_mov_b64 s[20:21], s[74:75]
	s_ashr_i32 s13, s12, 31
	s_lshl_b64 s[38:39], s[12:13], 2
	s_mov_b64 s[36:37], s[0:1]
	v_lshl_or_b32 v4, s12, 6, v218
	s_waitcnt lgkmcnt(0)
	s_add_u32 s20, s20, s38
	s_addc_u32 s21, s21, s39
	global_load_dword v2, v3, s[20:21]
	s_mov_b64 s[20:21], s[76:77]
	v_ashrrev_i32_e32 v5, 31, v4
	v_lshlrev_b64 v[6:7], 2, v[4:5]
	s_cmp_lg_u32 s34, 0
	s_waitcnt lgkmcnt(0)
	v_lshl_add_u64 v[22:23], s[20:21], 0, v[6:7]
	s_mov_b64 s[20:21], s[0:1]
	global_load_dword v5, v[22:23], off
	s_mov_b64 s[20:21], s[88:89]
	s_waitcnt lgkmcnt(0)
	v_lshl_add_u64 v[6:7], s[20:21], 0, v[6:7]
	global_load_dword v22, v[6:7], off
	s_waitcnt vmcnt(2)
	v_mul_f32_e32 v2, 0x3fb8aa3b, v2
	v_exp_f32_e32 v2, v2
	s_waitcnt vmcnt(1)
	v_mul_f32_e32 v6, v2, v5
	v_mul_f32_e32 v7, 0, v6
	v_add_f32_e32 v24, v6, v6
	v_mul_f32_e32 v25, 0x40400000, v6
	v_mul_f32_e32 v23, 0x3fb8aa3b, v6
	v_mul_f32_e32 v26, 4.0, v6
	v_mul_f32_e32 v27, 0x40a00000, v6
	v_mul_f32_e32 v28, 0x40c00000, v6
	s_waitcnt vmcnt(0)
	v_mul_f32_e32 v30, v2, v22
	v_mul_f32_e32 v2, 0, v30
	v_add_f32_e32 v32, v30, v30
	v_mul_f32_e32 v33, 0x40400000, v30
	v_mul_f32_e32 v31, 0.15915494, v30
	v_mul_f32_e32 v34, 4.0, v30
	v_mul_f32_e32 v35, 0x40a00000, v30
	v_mul_f32_e32 v36, 0x40c00000, v30
	v_mul_f32_e32 v38, 0.15915494, v2
	v_mul_f32_e32 v39, 0.15915494, v32
	v_mul_f32_e32 v40, 0.15915494, v33
	v_mul_f32_e32 v37, 0x40e00000, v30
	v_rndne_f32_e32 v31, v31
	v_mul_f32_e32 v41, 0.15915494, v34
	v_mul_f32_e32 v42, 0.15915494, v35
	v_mul_f32_e32 v43, 0.15915494, v36
	v_rndne_f32_e32 v38, v38
	v_rndne_f32_e32 v39, v39
	v_rndne_f32_e32 v40, v40
	v_mul_f32_e32 v7, 0x3fb8aa3b, v7
	v_mul_f32_e32 v24, 0x3fb8aa3b, v24
	v_mul_f32_e32 v25, 0x3fb8aa3b, v25
	v_mul_f32_e32 v44, 0.15915494, v37
	v_fma_f32 v31, v30, 0.15915494, -v31
	v_rndne_f32_e32 v41, v41
	v_rndne_f32_e32 v42, v42
	v_rndne_f32_e32 v43, v43
	v_fma_f32 v2, v2, 0.15915494, -v38
	v_fma_f32 v32, v32, 0.15915494, -v39
	v_fma_f32 v33, v33, 0.15915494, -v40
	v_exp_f32_e32 v23, v23
	v_mul_f32_e32 v26, 0x3fb8aa3b, v26
	v_mul_f32_e32 v27, 0x3fb8aa3b, v27
	v_mul_f32_e32 v28, 0x3fb8aa3b, v28
	v_exp_f32_e32 v7, v7
	v_exp_f32_e32 v24, v24
	v_exp_f32_e32 v25, v25
	v_rndne_f32_e32 v44, v44
	v_cos_f32_e32 v38, v31
	v_fma_f32 v34, v34, 0.15915494, -v41
	v_fma_f32 v35, v35, 0.15915494, -v42
	v_fma_f32 v36, v36, 0.15915494, -v43
	v_cos_f32_e32 v39, v2
	v_sin_f32_e32 v2, v2
	v_cos_f32_e32 v40, v32
	v_sin_f32_e32 v32, v32
	v_cos_f32_e32 v41, v33
	v_exp_f32_e32 v26, v26
	v_exp_f32_e32 v27, v27
	v_exp_f32_e32 v28, v28
	v_sin_f32_e32 v31, v31
	v_fma_f32 v37, v37, 0.15915494, -v44
	v_sin_f32_e32 v33, v33
	v_cos_f32_e32 v42, v34
	v_sin_f32_e32 v34, v34
	v_cos_f32_e32 v43, v35
	v_sin_f32_e32 v35, v35
	v_cos_f32_e32 v44, v36
	v_sin_f32_e32 v36, v36
	v_mul_f32_e32 v29, 0x40e00000, v6
	v_mul_f32_e32 v29, 0x3fb8aa3b, v29
	v_mul_f32_e32 v46, v23, v38
	v_mul_f32_e32 v39, v7, v39
	v_mul_f32_e32 v47, v7, v2
	v_mul_f32_e32 v2, v24, v40
	v_mul_f32_e32 v7, v24, v32
	v_mul_f32_e32 v24, v25, v41
	v_exp_f32_e32 v29, v29
	v_cos_f32_e32 v45, v37
	v_mul_f32_e32 v31, v23, v31
	v_mul_f32_e32 v25, v25, v33
	v_mul_f32_e32 v32, v26, v42
	v_mul_f32_e32 v26, v26, v34
	v_mul_f32_e32 v33, v27, v43
	v_mul_f32_e32 v27, v27, v35
	v_mul_f32_e32 v34, v28, v44
	v_mul_f32_e32 v28, v28, v36
	ds_write2st64_b32 v1, v39, v46 offset1:1
	ds_write2st64_b32 v1, v31, v7 offset0:18 offset1:19
	ds_write2st64_b32 v1, v2, v24 offset0:2 offset1:3
	ds_write2st64_b32 v1, v25, v26 offset0:20 offset1:21
	ds_write2st64_b32 v1, v32, v33 offset0:4 offset1:5
	ds_write2st64_b32 v1, v27, v28 offset0:22 offset1:23
	v_mul_f32_e32 v24, 0x41000000, v30
	v_mul_f32_e32 v25, 0.15915494, v24
; __device__ __forceinline__ void ssm_tables(int g, int part, LAS float* L, bf16* __restrict__ TE, bf16* __restrict__ FT, float* __restrict__ LAM16) {
;     ...
;         for (int k = 0; k <= 16; ++k) {
;             const float mag = __expf(are * dt * (float)k);
;             float rev = aim * dt * (float)k * 0.15915494309189535f; rev -= rintf(rev);
;             lkr[k * 64 + p] = mag * __builtin_amdgcn_cosf(rev); lki[k * 64 + p] = mag * __builtin_amdgcn_sinf(rev);
;         }
;         const float lbr = lkr[64 + p], lbi = lki[64 + p], den = are * are + aim * aim, nre = lbr - 1.f;
;         fr_[p] = (nre * are + lbi * aim) / den; fi_[p] = (lbi * are - nre * aim) / den;
;         if (part == 0) { LAM16[(g * 64 + p) * 2] = lkr[16 * 64 + p]; LAM16[(g * 64 + p) * 2 + 1] = lki[16 * 64 + p]; }
	v_mul_f32_e32 v7, 0x41000000, v6
	v_rndne_f32_e32 v25, v25
	v_mul_f32_e32 v7, 0x3fb8aa3b, v7
	v_fma_f32 v24, v24, 0.15915494, -v25
	v_mul_f32_e32 v27, 0x41100000, v30
	v_exp_f32_e32 v7, v7
	v_cos_f32_e32 v25, v24
	v_mul_f32_e32 v26, v29, v45
	v_sin_f32_e32 v24, v24
	v_mul_f32_e32 v28, 0.15915494, v27
	ds_write2st64_b32 v1, v34, v26 offset0:6 offset1:7
	v_mul_f32_e32 v26, 0x41100000, v6
	v_rndne_f32_e32 v28, v28
	v_sin_f32_e32 v2, v37
	v_mul_f32_e32 v26, 0x3fb8aa3b, v26
	v_fma_f32 v27, v27, 0.15915494, -v28
	v_exp_f32_e32 v26, v26
	v_cos_f32_e32 v28, v27
	v_mul_f32_e32 v25, v7, v25
	v_mul_f32_e32 v7, v7, v24
	v_sin_f32_e32 v24, v27
	v_mul_f32_e32 v2, v29, v2
	ds_write2st64_b32 v1, v2, v7 offset0:24 offset1:25
	v_mul_f32_e32 v2, v26, v28
	ds_write2st64_b32 v1, v25, v2 offset0:8 offset1:9
	v_mul_f32_e32 v2, v26, v24
	v_mul_f32_e32 v24, 0x41200000, v30
	v_mul_f32_e32 v25, 0.15915494, v24
	v_mul_f32_e32 v7, 0x41200000, v6
	v_rndne_f32_e32 v25, v25
	v_mul_f32_e32 v27, 0x41300000, v30
	v_mul_f32_e32 v7, 0x3fb8aa3b, v7
	v_fma_f32 v24, v24, 0.15915494, -v25
	v_mul_f32_e32 v28, 0.15915494, v27
	v_exp_f32_e32 v7, v7
	v_cos_f32_e32 v25, v24
	v_sin_f32_e32 v24, v24
	v_mul_f32_e32 v26, 0x41300000, v6
	v_rndne_f32_e32 v28, v28
	v_mul_f32_e32 v26, 0x3fb8aa3b, v26
	v_fma_f32 v27, v27, 0.15915494, -v28
	v_exp_f32_e32 v26, v26
	v_cos_f32_e32 v28, v27
	v_mul_f32_e32 v25, v7, v25
	v_mul_f32_e32 v7, v7, v24
	ds_write2st64_b32 v1, v2, v7 offset0:26 offset1:27
	v_sin_f32_e32 v7, v27
	v_mul_f32_e32 v27, 0x41400000, v30
	v_mul_f32_e32 v2, v26, v28
	v_mul_f32_e32 v28, 0.15915494, v27
	v_mul_f32_e32 v24, 0x41400000, v6
	v_rndne_f32_e32 v28, v28
	v_mul_f32_e32 v24, 0x3fb8aa3b, v24
	v_fma_f32 v27, v27, 0.15915494, -v28
	v_exp_f32_e32 v24, v24
	v_cos_f32_e32 v28, v27
	v_sin_f32_e32 v27, v27
	ds_write2st64_b32 v1, v25, v2 offset0:10 offset1:11
	v_mul_f32_e32 v2, v26, v7
	v_mul_f32_e32 v7, v24, v28
	v_mul_f32_e32 v24, v24, v27
	ds_write2st64_b32 v1, v2, v24 offset0:28 offset1:29
	v_mul_f32_e32 v24, 0x41500000, v30
	v_mul_f32_e32 v25, 0.15915494, v24
	v_mul_f32_e32 v27, 0x41600000, v30
	v_mul_f32_e32 v2, 0x41500000, v6
	v_rndne_f32_e32 v25, v25
	v_mul_f32_e32 v28, 0.15915494, v27
	v_mul_f32_e32 v2, 0x3fb8aa3b, v2
	v_fma_f32 v24, v24, 0.15915494, -v25
	v_mul_f32_e32 v26, 0x41600000, v6
	v_rndne_f32_e32 v28, v28
	v_exp_f32_e32 v2, v2
	v_cos_f32_e32 v25, v24
	v_sin_f32_e32 v24, v24
	v_mul_f32_e32 v26, 0x3fb8aa3b, v26
	v_fma_f32 v27, v27, 0.15915494, -v28
	v_exp_f32_e32 v26, v26
	v_cos_f32_e32 v28, v27
	v_mul_f32_e32 v25, v2, v25
	v_mul_f32_e32 v2, v2, v24
	v_sin_f32_e32 v24, v27
	v_mul_f32_e32 v27, 0x41700000, v30
	ds_write2st64_b32 v1, v7, v25 offset0:12 offset1:13
	v_mul_f32_e32 v7, v26, v28
	v_mul_f32_e32 v28, 0.15915494, v27
	v_mul_f32_e32 v25, 0x41700000, v6
	v_rndne_f32_e32 v28, v28
	v_mul_f32_e32 v25, 0x3fb8aa3b, v25
	v_fma_f32 v27, v27, 0.15915494, -v28
	v_exp_f32_e32 v25, v25
	v_cos_f32_e32 v28, v27
	v_mul_f32_e32 v24, v26, v24
	v_sin_f32_e32 v26, v27
	ds_write2st64_b32 v1, v2, v24 offset0:30 offset1:31
	v_mul_f32_e32 v2, v25, v28
	ds_write2st64_b32 v1, v7, v2 offset0:14 offset1:15
	v_mul_f32_e32 v2, 0x41800000, v6
	v_mul_f32_e32 v6, 0x41800000, v30
	v_fma_f32 v23, v23, v38, -1.0
	v_mul_f32_e32 v24, v25, v26
	v_mul_f32_e32 v7, 0.15915494, v6
	v_mul_f32_e32 v25, v22, v22
	v_mul_f32_e32 v26, v5, v23
	v_rndne_f32_e32 v7, v7
	v_fmac_f32_e32 v25, v5, v5
	v_fmac_f32_e32 v26, v22, v31
	v_mul_f32_e32 v2, 0x3fb8aa3b, v2
	v_fma_f32 v7, v6, 0.15915494, -v7
	v_div_scale_f32 v27, s[20:21], v25, v25, v26
	v_exp_f32_e32 v2, v2
	v_cos_f32_e32 v6, v7
	v_sin_f32_e32 v7, v7
	v_rcp_f32_e32 v28, v27
	v_mul_f32_e32 v22, v22, v23
	v_fma_f32 v5, v5, v31, -v22
	v_pk_mul_f32 v[6:7], v[2:3], v[6:7] op_sel_hi:[0,1]
	v_fma_f32 v2, -v27, v28, 1.0
	v_fmac_f32_e32 v28, v2, v28
	v_div_scale_f32 v2, vcc, v26, v25, v26
	v_div_scale_f32 v22, s[20:21], v25, v25, v5
	ds_write2st64_b32 v1, v6, v47 offset0:16 offset1:17
	ds_write2st64_b32 v1, v24, v7 offset0:32 offset1:33
	v_mul_f32_e32 v24, v2, v28
	v_rcp_f32_e32 v23, v22
	v_fma_f32 v29, -v27, v24, v2
	v_fmac_f32_e32 v24, v29, v28
	v_fma_f32 v2, -v27, v24, v2
	v_div_fmas_f32 v2, v2, v28, v24
	v_fma_f32 v24, -v22, v23, 1.0
	v_fmac_f32_e32 v23, v24, v23
	v_div_scale_f32 v24, vcc, v5, v25, v5
	v_div_fixup_f32 v2, v2, v25, v26
	v_mul_f32_e32 v26, v24, v23
	v_fma_f32 v27, -v22, v26, v24
	v_fmac_f32_e32 v26, v27, v23
	v_fma_f32 v22, -v22, v26, v24
	v_div_fmas_f32 v22, v22, v23, v26
	v_div_fixup_f32 v5, v22, v25, v5
	ds_write2st64_b32 v1, v2, v5 offset0:34 offset1:35
	s_cbranch_scc1 .LBB0_12
	s_load_dwordx2 s[18:19], s[18:19], 0xf0
	v_lshlrev_b32_e32 v4, 1, v4
	v_ashrrev_i32_e32 v5, 31, v4
	s_waitcnt lgkmcnt(0)
	v_lshl_add_u64 v[4:5], v[4:5], 2, s[18:19]
	v_add_co_u32_e32 v4, vcc, 0x54000, v4
	s_nop 1
	v_addc_co_u32_e32 v5, vcc, 0, v5, vcc
	global_store_dwordx2 v[4:5], v[6:7], off

; #define LAS __attribute__((address_space(3)))
; #define INP(k) ((const float*)(GAS const float*)KARG64(8 * (k)))
; #define WSP() ((unsigned char*)(GAS unsigned char*)KARG64(240))
; __global__ void __launch_bounds__(NWAVES * 64, 2) hybrid_fwd(Params P) {
;     ...
;         const float gqm = fabsf(INP(14)[lane]), gkm = fabsf(INP(15)[lane]);
;         float gq = gqm, gk = gkm;
; #pragma unroll
;         for (int o = 1; o < 64; o <<= 1) { gq = fmaxf(gq, __shfl_xor(gq, o)); gk = fmaxf(gk, __shfl_xor(gk, o)); }
;         const float Rb = 2.2f * 8.f * gq * gk + 110.f;
;         volatile LAS int* qw = (volatile LAS int*)(lds + LDS_X + 512);
;         unsigned* qctr = (unsigned*)(WSP() + WS_BAR) + 4000;
;         const float lam = __expf(wave_sum(INP(16)[lane] * INP(17)[lane])) - __expf(wave_sum(INP(18)[lane] * INP(19)[lane])) + 0.2f;
;         for (;;) {
;             if (tid == 0) *qw = (int)atomicAdd(qctr, 1u);
.LBB0_554:
	s_load_dwordx2 s[60:61], s[0:1], 0x70
	s_load_dwordx2 s[62:63], s[0:1], 0x78
	s_load_dwordx2 s[64:65], s[0:1], 0x80
	s_load_dwordx2 s[66:67], s[0:1], 0x88
	s_load_dwordx2 s[68:69], s[0:1], 0x90
	s_load_dwordx2 s[70:71], s[0:1], 0x98
	s_waitcnt lgkmcnt(0)
	s_mov_b64 s[4:5], s[0:1]
	s_mov_b64 s[4:5], s[60:61]
	v_lshlrev_b32_e32 v1, 2, v174
	s_mov_b64 s[6:7], s[0:1]
	s_mov_b64 s[8:9], s[0:1]
	v_mbcnt_lo_u32_b32 v9, -1, 0
	s_waitcnt lgkmcnt(0)
	global_load_dword v2, v1, s[4:5]
	s_mov_b64 s[4:5], s[62:63]
	s_mov_b64 s[6:7], s[0:1]
	v_mbcnt_hi_u32_b32 v9, -1, v9
	v_and_b32_e32 v10, 64, v9
	v_xor_b32_e32 v11, 1, v9
	s_waitcnt lgkmcnt(0)
	global_load_dword v3, v1, s[4:5]
	s_load_dwordx2 s[4:5], s[6:7], 0xf0
	s_mov_b64 s[6:7], s[64:65]
	s_mov_b64 s[8:9], s[0:1]
	v_add_u32_e32 v10, 64, v10
	v_xor_b32_e32 v12, 2, v9
	v_cmp_lt_i32_e32 vcc, v11, v10
	s_waitcnt lgkmcnt(0)
	global_load_dword v4, v1, s[6:7]
	s_mov_b64 s[6:7], s[66:67]
	s_mov_b64 s[8:9], s[0:1]
	v_xor_b32_e32 v13, 4, v9
	v_cndmask_b32_e32 v11, v9, v11, vcc
	v_cmp_lt_i32_e32 vcc, v12, v10
	s_waitcnt lgkmcnt(0)
	global_load_dword v6, v1, s[6:7]
	s_mov_b64 s[6:7], s[68:69]
	s_mov_b64 s[8:9], s[0:1]
	v_xor_b32_e32 v14, 8, v9
	v_cndmask_b32_e32 v12, v9, v12, vcc
	v_cmp_lt_i32_e32 vcc, v13, v10
	s_waitcnt lgkmcnt(0)
	global_load_dword v7, v1, s[6:7]
	s_mov_b64 s[6:7], s[70:71]
	v_xor_b32_e32 v15, 16, v9
	v_cndmask_b32_e32 v13, v9, v13, vcc
	v_cmp_lt_i32_e32 vcc, v14, v10
	v_xor_b32_e32 v16, 32, v9
	s_waitcnt lgkmcnt(0)
	global_load_dword v8, v1, s[6:7]
	v_cndmask_b32_e32 v14, v9, v14, vcc
	v_cmp_lt_i32_e32 vcc, v15, v10
	s_add_u32 s4, s4, 0x83e80
	s_addc_u32 s5, s5, 0
	v_cndmask_b32_e32 v15, v9, v15, vcc
	v_cmp_lt_i32_e32 vcc, v16, v10
	v_lshlrev_b32_e32 v10, 2, v11
	v_lshlrev_b32_e32 v11, 2, v12
	v_lshlrev_b32_e32 v12, 2, v13
	v_lshlrev_b32_e32 v13, 2, v14
	v_lshlrev_b32_e32 v14, 2, v15
	v_cndmask_b32_e32 v9, v9, v16, vcc
	v_lshlrev_b32_e32 v9, 2, v9
	s_add_i32 s33, 0, 0x20200
	s_mov_b32 s83, 0
	v_mov_b32_e32 v5, 0
	s_movk_i32 s76, 0x2400
	s_mov_b32 s77, 0x7ffffc
	s_mov_b64 s[84:85], 0x10000
	v_mov_b32_e32 v1, 0x358637bd
	v_mov_b32_e32 v175, 0x46000000
	v_mov_b32_e32 v188, 0x404000
	v_mov_b32_e32 v189, 0x4800
	v_mov_b32_e32 v190, 0xf149f2ca
	v_writelane_b32 v240, s4, 12
	v_mov_b32_e32 v191, s33
	v_mov_b32_e32 v193, 0x8000
	v_writelane_b32 v240, s5, 13
	s_waitcnt vmcnt(0)
	v_and_b32_e32 v15, 0x7fffffff, v2
	ds_bpermute_b32 v15, v10, v15
	v_max_f32_e64 v2, |v2|, |v2|
	s_waitcnt lgkmcnt(0)
	v_max_f32_e32 v15, v15, v15
	v_and_b32_e32 v16, 0x7fffffff, v3
	ds_bpermute_b32 v16, v10, v16
	v_max_f32_e32 v2, v2, v15
	ds_bpermute_b32 v15, v11, v2
	v_max_f32_e64 v3, |v3|, |v3|
	s_waitcnt lgkmcnt(1)
	v_max_f32_e32 v16, v16, v16
	v_max_f32_e32 v3, v3, v16
	s_waitcnt lgkmcnt(0)
	v_max_f32_e32 v15, v15, v15
	ds_bpermute_b32 v16, v11, v3
	v_max_f32_e32 v2, v2, v15
	ds_bpermute_b32 v15, v12, v2
	s_waitcnt lgkmcnt(1)
	v_max_f32_e32 v16, v16, v16
	v_max_f32_e32 v3, v3, v16
	v_mul_f32_e32 v17, v4, v6
	s_waitcnt lgkmcnt(0)
	v_max_f32_e32 v15, v15, v15
	ds_bpermute_b32 v16, v10, v17
	ds_bpermute_b32 v17, v12, v3
	v_max_f32_e32 v2, v2, v15
	ds_bpermute_b32 v15, v13, v2
	s_waitcnt lgkmcnt(2)
	v_fmac_f32_e32 v16, v4, v6
	s_waitcnt lgkmcnt(1)
	v_max_f32_e32 v4, v17, v17
	v_max_f32_e32 v3, v3, v4
	s_waitcnt lgkmcnt(0)
	v_max_f32_e32 v4, v15, v15
	ds_bpermute_b32 v6, v11, v16
	v_max_f32_e32 v2, v2, v4
	ds_bpermute_b32 v4, v13, v3
	v_mul_f32_e32 v15, v7, v8
	ds_bpermute_b32 v10, v10, v15
	ds_bpermute_b32 v15, v14, v2
	s_waitcnt lgkmcnt(3)
	v_add_f32_e32 v6, v16, v6
	ds_bpermute_b32 v16, v12, v6
	s_waitcnt lgkmcnt(3)
	v_max_f32_e32 v4, v4, v4
	s_waitcnt lgkmcnt(2)
	v_fmac_f32_e32 v10, v7, v8
	ds_bpermute_b32 v7, v11, v10
	v_max_f32_e32 v3, v3, v4
	s_waitcnt lgkmcnt(2)
	v_max_f32_e32 v4, v15, v15
	v_max_f32_e32 v2, v2, v4
	ds_bpermute_b32 v4, v14, v3
	s_waitcnt lgkmcnt(1)
	v_add_f32_e32 v7, v10, v7
	ds_bpermute_b32 v8, v12, v7
	v_add_f32_e32 v6, v6, v16
	ds_bpermute_b32 v11, v13, v6
	s_waitcnt lgkmcnt(2)
	v_max_f32_e32 v4, v4, v4
	v_max_f32_e32 v3, v3, v4
	s_waitcnt lgkmcnt(1)
	v_add_f32_e32 v7, v7, v8
	ds_bpermute_b32 v8, v13, v7
	s_waitcnt lgkmcnt(1)
	v_add_f32_e32 v4, v6, v11
	ds_bpermute_b32 v6, v14, v4
	ds_bpermute_b32 v10, v9, v2
	s_waitcnt lgkmcnt(2)
	v_add_f32_e32 v7, v7, v8
	ds_bpermute_b32 v8, v14, v7
	s_waitcnt lgkmcnt(2)
	v_add_f32_e32 v4, v4, v6
	ds_bpermute_b32 v6, v9, v4
	s_waitcnt lgkmcnt(2)
	v_max_f32_e32 v10, v10, v10
	v_max_f32_e32 v2, v2, v10
	s_waitcnt lgkmcnt(1)
	v_add_f32_e32 v7, v7, v8
	ds_bpermute_b32 v8, v9, v7
	ds_bpermute_b32 v10, v9, v3
	s_waitcnt lgkmcnt(2)
	v_add_f32_e32 v4, v4, v6
	v_mul_f32_e32 v4, 0x3fb8aa3b, v4
	v_exp_f32_e32 v4, v4
	s_waitcnt lgkmcnt(1)
	v_add_f32_e32 v6, v7, v8
	v_mul_f32_e32 v6, 0x3fb8aa3b, v6
	v_exp_f32_e32 v6, v6
	s_waitcnt lgkmcnt(0)
	v_max_f32_e32 v7, v10, v10
	v_mul_f32_e32 v2, 0x418ccccd, v2
	v_max_f32_e32 v3, v3, v7
	v_fmaak_f32 v192, v3, v2, 0x42dc0000
	v_sub_f32_e32 v2, v4, v6
	v_add_f32_e32 v176, 0x3e4ccccd, v2
	v_mov_b32_e32 v177, v176
	v_readlane_b32 s98, v240, 3
	s_nop 3
	s_cmp_lg_u32 s98, 0
	s_cbranch_scc1 .Latk_a
	v_readlane_b32 s100, v240, 12
	v_readlane_b32 s101, v240, 13
	s_mov_b64 s[98:99], exec
	s_mov_b64 exec, 1
	v_mov_b32_e32 v244, 1
	v_mov_b32_e32 v245, 0
	s_nop 4
	global_atomic_add v244, v245, v244, s[100:101] sc0
	s_mov_b64 exec, s[98:99]
